# attention: one barrier per K/V tile; wave group B runs softmax(kt-1) before its MFMA segment so the two waves of a SIMD alternate MFMA and softmax without a mid-tile barrier
# speedup vs baseline: 1.0003x; 1.0003x over previous
.Lat_loop:
	s_cmp_eq_u32 s35, 0
	s_cbranch_scc1 .Lat_yb_skip
	s_cmp_eq_u32 s22, 0
	s_cbranch_scc1 .Lat_yb_skip
	s_add_i32 s96, s22, -1
	s_cmp_gt_i32 s96, s25
	s_cbranch_scc1 .Lat_y_skip_b
	s_nop 7
	s_waitcnt lgkmcnt(0)
	v_mul_f32_e32 v66, v66, v162
	v_mul_f32_e32 v67, v67, v163
	v_mul_f32_e32 v68, v68, v164
	v_mul_f32_e32 v69, v69, v165
	v_mul_f32_e32 v70, v70, v166
	v_mul_f32_e32 v71, v71, v167
	v_mul_f32_e32 v72, v72, v168
	v_mul_f32_e32 v73, v73, v169
	v_mul_f32_e32 v74, v74, v170
	v_mul_f32_e32 v75, v75, v171
	v_mul_f32_e32 v76, v76, v172
	v_mul_f32_e32 v77, v77, v173
	v_mul_f32_e32 v78, v78, v174
	v_mul_f32_e32 v79, v79, v175
	v_mul_f32_e32 v80, v80, v176
	v_mul_f32_e32 v81, v81, v177
	v_mul_f32_e32 v82, v82, v178
	v_mul_f32_e32 v83, v83, v179
	v_mul_f32_e32 v84, v84, v180
	v_mul_f32_e32 v85, v85, v181
	v_mul_f32_e32 v86, v86, v182
	v_mul_f32_e32 v87, v87, v183
	v_mul_f32_e32 v88, v88, v184
	v_mul_f32_e32 v89, v89, v185
	v_mul_f32_e32 v90, v90, v186
	v_mul_f32_e32 v91, v91, v187
	v_mul_f32_e32 v92, v92, v188
	v_mul_f32_e32 v93, v93, v189
	v_mul_f32_e32 v94, v94, v190
	v_mul_f32_e32 v95, v95, v191
	v_mul_f32_e32 v96, v96, v192
	v_mul_f32_e32 v97, v97, v193
	s_cmp_lg_u32 s96, s25
	s_cbranch_scc1 .Lat_y_nogate_b
	v_add_u32_e32 v194, s38, v234
	v_lshlrev_b32_e32 v194, 11, v194
	v_lshl_add_u32 v194, v241, 3, v194
	global_load_dwordx2 v[162:163], v194, s[6:7] offset:0
	global_load_dwordx2 v[164:165], v194, s[6:7] offset:16
	global_load_dwordx2 v[166:167], v194, s[6:7] offset:32
	global_load_dwordx2 v[168:169], v194, s[6:7] offset:48
	global_load_dwordx2 v[170:171], v194, s[6:7] offset:64
	global_load_dwordx2 v[172:173], v194, s[6:7] offset:80
	global_load_dwordx2 v[174:175], v194, s[6:7] offset:96
	global_load_dwordx2 v[176:177], v194, s[6:7] offset:112
	global_load_dwordx2 v[178:179], v194, s[6:7] offset:128
	global_load_dwordx2 v[180:181], v194, s[6:7] offset:144
	global_load_dwordx2 v[182:183], v194, s[6:7] offset:160
	global_load_dwordx2 v[184:185], v194, s[6:7] offset:176
	global_load_dwordx2 v[186:187], v194, s[6:7] offset:192
	global_load_dwordx2 v[188:189], v194, s[6:7] offset:208
	global_load_dwordx2 v[190:191], v194, s[6:7] offset:224
	global_load_dwordx2 v[192:193], v194, s[6:7] offset:240
.Lat_y_nogate_b:
	s_lshl_b32 s65, s96, 6
	s_add_i32 s72, s65, 63
	s_cmp_le_i32 s72, s64
	s_cbranch_scc1 .Lat_y_nomask_b
	v_subrev_u32_e32 v242, s65, v239
	v_cmp_gt_i32_e32 vcc, 0, v242
	v_cmp_gt_i32_e64 s[36:37], 1, v242
	s_nop 0
	v_cndmask_b32_e32 v66, v66, v238, vcc
	v_cndmask_b32_e64 v67, v67, v238, s[36:37]
	v_cmp_gt_i32_e32 vcc, 2, v242
	v_cmp_gt_i32_e64 s[36:37], 3, v242
	s_nop 0
	v_cndmask_b32_e32 v68, v68, v238, vcc
	v_cndmask_b32_e64 v69, v69, v238, s[36:37]
	v_cmp_gt_i32_e32 vcc, 8, v242
	v_cmp_gt_i32_e64 s[36:37], 9, v242
	s_nop 0
	v_cndmask_b32_e32 v70, v70, v238, vcc
	v_cndmask_b32_e64 v71, v71, v238, s[36:37]
	v_cmp_gt_i32_e32 vcc, 10, v242
	v_cmp_gt_i32_e64 s[36:37], 11, v242
	s_nop 0
	v_cndmask_b32_e32 v72, v72, v238, vcc
	v_cndmask_b32_e64 v73, v73, v238, s[36:37]
	v_cmp_gt_i32_e32 vcc, 16, v242
	v_cmp_gt_i32_e64 s[36:37], 17, v242
	s_nop 0
	v_cndmask_b32_e32 v74, v74, v238, vcc
	v_cndmask_b32_e64 v75, v75, v238, s[36:37]
	v_cmp_gt_i32_e32 vcc, 18, v242
	v_cmp_gt_i32_e64 s[36:37], 19, v242
	s_nop 0
	v_cndmask_b32_e32 v76, v76, v238, vcc
	v_cndmask_b32_e64 v77, v77, v238, s[36:37]
	v_cmp_gt_i32_e32 vcc, 24, v242
	v_cmp_gt_i32_e64 s[36:37], 25, v242
	s_nop 0
	v_cndmask_b32_e32 v78, v78, v238, vcc
	v_cndmask_b32_e64 v79, v79, v238, s[36:37]
	v_cmp_gt_i32_e32 vcc, 26, v242
	v_cmp_gt_i32_e64 s[36:37], 27, v242
	s_nop 0
	v_cndmask_b32_e32 v80, v80, v238, vcc
	v_cndmask_b32_e64 v81, v81, v238, s[36:37]
	v_cmp_gt_i32_e32 vcc, 32, v242
	v_cmp_gt_i32_e64 s[36:37], 33, v242
	s_nop 0
	v_cndmask_b32_e32 v82, v82, v238, vcc
	v_cndmask_b32_e64 v83, v83, v238, s[36:37]
	v_cmp_gt_i32_e32 vcc, 34, v242
	v_cmp_gt_i32_e64 s[36:37], 35, v242
	s_nop 0
	v_cndmask_b32_e32 v84, v84, v238, vcc
	v_cndmask_b32_e64 v85, v85, v238, s[36:37]
	v_cmp_gt_i32_e32 vcc, 40, v242
	v_cmp_gt_i32_e64 s[36:37], 41, v242
	s_nop 0
	v_cndmask_b32_e32 v86, v86, v238, vcc
	v_cndmask_b32_e64 v87, v87, v238, s[36:37]
	v_cmp_gt_i32_e32 vcc, 42, v242
	v_cmp_gt_i32_e64 s[36:37], 43, v242
	s_nop 0
	v_cndmask_b32_e32 v88, v88, v238, vcc
	v_cndmask_b32_e64 v89, v89, v238, s[36:37]
	v_cmp_gt_i32_e32 vcc, 48, v242
	v_cmp_gt_i32_e64 s[36:37], 49, v242
	s_nop 0
	v_cndmask_b32_e32 v90, v90, v238, vcc
	v_cndmask_b32_e64 v91, v91, v238, s[36:37]
	v_cmp_gt_i32_e32 vcc, 50, v242
	v_cmp_gt_i32_e64 s[36:37], 51, v242
	s_nop 0
	v_cndmask_b32_e32 v92, v92, v238, vcc
	v_cndmask_b32_e64 v93, v93, v238, s[36:37]
	v_cmp_gt_i32_e32 vcc, 56, v242
	v_cmp_gt_i32_e64 s[36:37], 57, v242
	s_nop 0
	v_cndmask_b32_e32 v94, v94, v238, vcc
	v_cndmask_b32_e64 v95, v95, v238, s[36:37]
	v_cmp_gt_i32_e32 vcc, 58, v242
	v_cmp_gt_i32_e64 s[36:37], 59, v242
	s_nop 0
	v_cndmask_b32_e32 v96, v96, v238, vcc
	v_cndmask_b32_e64 v97, v97, v238, s[36:37]

.Lat_y_skip_b:
.Lat_yb_skip:
	s_add_i32 s65, s22, 1
	s_cmp_ge_u32 s65, s23
	s_cbranch_scc1 .Lat_x_nostore
	s_add_i32 s72, s24, 1
	s_cmp_eq_u32 s72, 3
	s_cselect_b32 s72, 0, s72
	s_mul_i32 s36, s72, 0x6400
	s_mul_i32 s37, s72, 0x4400
	s_lshl_b32 s39, s72, 8

.Lat_nosq6:
.Lat_x_nopf:
	s_cmp_lg_u32 s35, 0
	s_cbranch_scc1 .Lat_ya_skip
	s_mov_b32 s96, s22
	s_cmp_gt_i32 s96, s25
	s_cbranch_scc1 .Lat_y_skip_a
	s_nop 7
	s_waitcnt lgkmcnt(0)
	v_mul_f32_e32 v66, v66, v162
	v_mul_f32_e32 v67, v67, v163
	v_mul_f32_e32 v68, v68, v164
	v_mul_f32_e32 v69, v69, v165
	v_mul_f32_e32 v70, v70, v166
	v_mul_f32_e32 v71, v71, v167
	v_mul_f32_e32 v72, v72, v168
	v_mul_f32_e32 v73, v73, v169
	v_mul_f32_e32 v74, v74, v170
	v_mul_f32_e32 v75, v75, v171
	v_mul_f32_e32 v76, v76, v172
	v_mul_f32_e32 v77, v77, v173
	v_mul_f32_e32 v78, v78, v174
	v_mul_f32_e32 v79, v79, v175
	v_mul_f32_e32 v80, v80, v176
	v_mul_f32_e32 v81, v81, v177
	v_mul_f32_e32 v82, v82, v178
	v_mul_f32_e32 v83, v83, v179
	v_mul_f32_e32 v84, v84, v180
	v_mul_f32_e32 v85, v85, v181
	v_mul_f32_e32 v86, v86, v182
	v_mul_f32_e32 v87, v87, v183
	v_mul_f32_e32 v88, v88, v184
	v_mul_f32_e32 v89, v89, v185
	v_mul_f32_e32 v90, v90, v186
	v_mul_f32_e32 v91, v91, v187
	v_mul_f32_e32 v92, v92, v188
	v_mul_f32_e32 v93, v93, v189
	v_mul_f32_e32 v94, v94, v190
	v_mul_f32_e32 v95, v95, v191
	v_mul_f32_e32 v96, v96, v192
	v_mul_f32_e32 v97, v97, v193
	s_cmp_lg_u32 s96, s25
	s_cbranch_scc1 .Lat_y_nogate_a
	v_add_u32_e32 v194, s38, v234
	v_lshlrev_b32_e32 v194, 11, v194
	v_lshl_add_u32 v194, v241, 3, v194
	global_load_dwordx2 v[162:163], v194, s[6:7] offset:0
	global_load_dwordx2 v[164:165], v194, s[6:7] offset:16
	global_load_dwordx2 v[166:167], v194, s[6:7] offset:32
	global_load_dwordx2 v[168:169], v194, s[6:7] offset:48
	global_load_dwordx2 v[170:171], v194, s[6:7] offset:64
	global_load_dwordx2 v[172:173], v194, s[6:7] offset:80
	global_load_dwordx2 v[174:175], v194, s[6:7] offset:96
	global_load_dwordx2 v[176:177], v194, s[6:7] offset:112
	global_load_dwordx2 v[178:179], v194, s[6:7] offset:128
	global_load_dwordx2 v[180:181], v194, s[6:7] offset:144
	global_load_dwordx2 v[182:183], v194, s[6:7] offset:160
	global_load_dwordx2 v[184:185], v194, s[6:7] offset:176
	global_load_dwordx2 v[186:187], v194, s[6:7] offset:192
	global_load_dwordx2 v[188:189], v194, s[6:7] offset:208
	global_load_dwordx2 v[190:191], v194, s[6:7] offset:224
	global_load_dwordx2 v[192:193], v194, s[6:7] offset:240

.Lat_y_norescale_a:
	v_fma_f32 v66, v235, v66, -v195
	v_fma_f32 v67, v235, v67, -v195
	v_exp_f32_e32 v66, v66
	v_fma_f32 v68, v235, v68, -v195
	v_exp_f32_e32 v67, v67
	v_fma_f32 v69, v235, v69, -v195
	v_exp_f32_e32 v68, v68
	v_fma_f32 v70, v235, v70, -v195
	v_exp_f32_e32 v69, v69
	v_fma_f32 v71, v235, v71, -v195
	v_exp_f32_e32 v70, v70
	v_fma_f32 v72, v235, v72, -v195
	v_exp_f32_e32 v71, v71
	v_fma_f32 v73, v235, v73, -v195
	v_exp_f32_e32 v72, v72
	v_fma_f32 v74, v235, v74, -v195
	v_exp_f32_e32 v73, v73
	v_fma_f32 v75, v235, v75, -v195
	v_exp_f32_e32 v74, v74
	v_fma_f32 v76, v235, v76, -v195
	v_exp_f32_e32 v75, v75
	v_fma_f32 v77, v235, v77, -v195
	v_exp_f32_e32 v76, v76
	v_fma_f32 v78, v235, v78, -v195
	v_exp_f32_e32 v77, v77
	v_fma_f32 v79, v235, v79, -v195
	v_exp_f32_e32 v78, v78
	v_fma_f32 v80, v235, v80, -v195
	v_exp_f32_e32 v79, v79
	v_fma_f32 v81, v235, v81, -v195
	v_exp_f32_e32 v80, v80
	v_fma_f32 v82, v235, v82, -v195
	v_exp_f32_e32 v81, v81
	v_fma_f32 v83, v235, v83, -v195
	v_exp_f32_e32 v82, v82
	v_fma_f32 v84, v235, v84, -v195
	v_exp_f32_e32 v83, v83
	v_fma_f32 v85, v235, v85, -v195
	v_exp_f32_e32 v84, v84
	v_fma_f32 v86, v235, v86, -v195
	v_exp_f32_e32 v85, v85
	v_fma_f32 v87, v235, v87, -v195
	v_exp_f32_e32 v86, v86
	v_fma_f32 v88, v235, v88, -v195
	v_exp_f32_e32 v87, v87
	v_fma_f32 v89, v235, v89, -v195
	v_exp_f32_e32 v88, v88
	v_fma_f32 v90, v235, v90, -v195
	v_exp_f32_e32 v89, v89
	v_fma_f32 v91, v235, v91, -v195
	v_exp_f32_e32 v90, v90
	v_fma_f32 v92, v235, v92, -v195
	v_exp_f32_e32 v91, v91
	v_fma_f32 v93, v235, v93, -v195
	v_exp_f32_e32 v92, v92
	v_fma_f32 v94, v235, v94, -v195
	v_exp_f32_e32 v93, v93
	v_fma_f32 v95, v235, v95, -v195
	v_exp_f32_e32 v94, v94
	v_fma_f32 v96, v235, v96, -v195
	v_exp_f32_e32 v95, v95
	v_fma_f32 v97, v235, v97, -v195
	v_exp_f32_e32 v96, v96
	v_exp_f32_e32 v97, v97
	s_nop 0
	v_add_f32_e32 v243, v66, v70
	v_add_f32_e32 v244, v67, v71
	v_add_f32_e32 v245, v68, v72
	v_add_f32_e32 v246, v69, v73
	v_add_f32_e32 v243, v243, v74
	v_add_f32_e32 v244, v244, v75
	v_add_f32_e32 v245, v245, v76
	v_add_f32_e32 v246, v246, v77
	v_add_f32_e32 v243, v243, v78
	v_add_f32_e32 v244, v244, v79
	v_add_f32_e32 v245, v245, v80
	v_add_f32_e32 v246, v246, v81
	v_add_f32_e32 v243, v243, v82
	v_add_f32_e32 v244, v244, v83
	v_add_f32_e32 v245, v245, v84
	v_add_f32_e32 v246, v246, v85
	v_add_f32_e32 v243, v243, v86
	v_add_f32_e32 v244, v244, v87
	v_add_f32_e32 v245, v245, v88
	v_add_f32_e32 v246, v246, v89
	v_add_f32_e32 v243, v243, v90
	v_add_f32_e32 v244, v244, v91
	v_add_f32_e32 v245, v245, v92
	v_add_f32_e32 v246, v246, v93
	v_add_f32_e32 v243, v243, v94
	v_add_f32_e32 v244, v244, v95
	v_add_f32_e32 v245, v245, v96
	v_add_f32_e32 v246, v246, v97
	v_add_f32_e32 v243, v243, v244
	v_add_f32_e32 v245, v245, v246
	v_add_f32_e32 v243, v243, v245
	v_mov_b32_e32 v236, v195
	v_fma_f32 v237, v237, v248, v243
	v_cvt_pk_bf16_f32 v146, v66, v67
	v_cvt_pk_bf16_f32 v147, v68, v69
	v_cvt_pk_bf16_f32 v148, v70, v71
	v_cvt_pk_bf16_f32 v149, v72, v73
	v_cvt_pk_bf16_f32 v150, v74, v75
	v_cvt_pk_bf16_f32 v151, v76, v77
	v_cvt_pk_bf16_f32 v152, v78, v79
	v_cvt_pk_bf16_f32 v153, v80, v81
	v_cvt_pk_bf16_f32 v154, v82, v83
	v_cvt_pk_bf16_f32 v155, v84, v85
	v_cvt_pk_bf16_f32 v156, v86, v87
	v_cvt_pk_bf16_f32 v157, v88, v89
	v_cvt_pk_bf16_f32 v158, v90, v91
	v_cvt_pk_bf16_f32 v159, v92, v93
	v_cvt_pk_bf16_f32 v160, v94, v95
	v_cvt_pk_bf16_f32 v161, v96, v97
.Lat_y_skip_a:
.Lat_ya_skip:
	s_barrier
.Lat_yz:
	s_add_i32 s22, s22, 1
	s_add_i32 s24, s24, 1
	s_cmp_eq_u32 s24, 3
	s_cselect_b32 s24, 0, s24
	s_cmp_lt_u32 s22, s23
	s_cbranch_scc1 .Lat_loop
	s_cmp_eq_u32 s35, 0
	s_cbranch_scc1 .Lat_yc_skip
	s_add_i32 s96, s23, -1
	s_cmp_gt_i32 s96, s25
	s_cbranch_scc1 .Lat_y_skip_c
	s_nop 7
	s_waitcnt lgkmcnt(0)
	v_mul_f32_e32 v66, v66, v162
	v_mul_f32_e32 v67, v67, v163
	v_mul_f32_e32 v68, v68, v164
	v_mul_f32_e32 v69, v69, v165
	v_mul_f32_e32 v70, v70, v166
	v_mul_f32_e32 v71, v71, v167
	v_mul_f32_e32 v72, v72, v168
	v_mul_f32_e32 v73, v73, v169
	v_mul_f32_e32 v74, v74, v170
	v_mul_f32_e32 v75, v75, v171
	v_mul_f32_e32 v76, v76, v172
	v_mul_f32_e32 v77, v77, v173
	v_mul_f32_e32 v78, v78, v174
	v_mul_f32_e32 v79, v79, v175
	v_mul_f32_e32 v80, v80, v176
	v_mul_f32_e32 v81, v81, v177
	v_mul_f32_e32 v82, v82, v178
	v_mul_f32_e32 v83, v83, v179
	v_mul_f32_e32 v84, v84, v180
	v_mul_f32_e32 v85, v85, v181
	v_mul_f32_e32 v86, v86, v182
	v_mul_f32_e32 v87, v87, v183
	v_mul_f32_e32 v88, v88, v184
	v_mul_f32_e32 v89, v89, v185
	v_mul_f32_e32 v90, v90, v186
	v_mul_f32_e32 v91, v91, v187
	v_mul_f32_e32 v92, v92, v188
	v_mul_f32_e32 v93, v93, v189
	v_mul_f32_e32 v94, v94, v190
	v_mul_f32_e32 v95, v95, v191
	v_mul_f32_e32 v96, v96, v192
	v_mul_f32_e32 v97, v97, v193
	s_cmp_lg_u32 s96, s25
	s_cbranch_scc1 .Lat_y_nogate_c
	v_add_u32_e32 v194, s38, v234
	v_lshlrev_b32_e32 v194, 11, v194
	v_lshl_add_u32 v194, v241, 3, v194
	global_load_dwordx2 v[162:163], v194, s[6:7] offset:0
	global_load_dwordx2 v[164:165], v194, s[6:7] offset:16
	global_load_dwordx2 v[166:167], v194, s[6:7] offset:32
	global_load_dwordx2 v[168:169], v194, s[6:7] offset:48
	global_load_dwordx2 v[170:171], v194, s[6:7] offset:64
	global_load_dwordx2 v[172:173], v194, s[6:7] offset:80
	global_load_dwordx2 v[174:175], v194, s[6:7] offset:96
	global_load_dwordx2 v[176:177], v194, s[6:7] offset:112
	global_load_dwordx2 v[178:179], v194, s[6:7] offset:128
	global_load_dwordx2 v[180:181], v194, s[6:7] offset:144
	global_load_dwordx2 v[182:183], v194, s[6:7] offset:160
	global_load_dwordx2 v[184:185], v194, s[6:7] offset:176
	global_load_dwordx2 v[186:187], v194, s[6:7] offset:192
	global_load_dwordx2 v[188:189], v194, s[6:7] offset:208
	global_load_dwordx2 v[190:191], v194, s[6:7] offset:224
	global_load_dwordx2 v[192:193], v194, s[6:7] offset:240

.Lat_y_skip_c:
.Lat_yc_skip:
	s_add_i32 s65, s23, -1
	s_cmp_gt_i32 s65, s25
	s_cbranch_scc1 .Lat_f_nopv
	s_add_i32 s72, s24, 2
	s_cmp_ge_u32 s72, 3
	s_cbranch_scc0 .Lat_f_pvb
	s_sub_i32 s72, s72, 3
.Lat_f_pvb:
	s_mul_i32 s37, s72, 0x4400
	v_add_u32_e32 v243, s37, v231
	v_add_u32_e32 v244, 0x1100, v243
	v_add_u32_e32 v245, 0x2200, v243
	v_add_u32_e32 v246, 0x3300, v243
	ds_read2_b64 v[66:69], v243 offset0:0 offset1:2
	ds_read2_b64 v[70:73], v244 offset0:0 offset1:2
	ds_read2_b64 v[74:77], v245 offset0:0 offset1:2
	ds_read2_b64 v[78:81], v246 offset0:0 offset1:2
	ds_read2_b64 v[82:85], v243 offset0:4 offset1:6
	ds_read2_b64 v[86:89], v244 offset0:4 offset1:6
	ds_read2_b64 v[90:93], v245 offset0:4 offset1:6
	s_waitcnt lgkmcnt(6)
	v_mfma_f32_32x32x16_bf16 v[2:17], v[66:69], v[146:149], v[2:17]
	ds_read2_b64 v[94:97], v246 offset0:4 offset1:6
	s_waitcnt lgkmcnt(6)
	v_mfma_f32_32x32x16_bf16 v[18:33], v[70:73], v[146:149], v[18:33]
	ds_read2_b64 v[66:69], v243 offset0:8 offset1:10
	s_waitcnt lgkmcnt(6)
	v_mfma_f32_32x32x16_bf16 v[34:49], v[74:77], v[146:149], v[34:49]
	ds_read2_b64 v[70:73], v244 offset0:8 offset1:10
	s_waitcnt lgkmcnt(6)
	v_mfma_f32_32x32x16_bf16 v[50:65], v[78:81], v[146:149], v[50:65]
	ds_read2_b64 v[74:77], v245 offset0:8 offset1:10
	s_waitcnt lgkmcnt(6)
	v_mfma_f32_32x32x16_bf16 v[2:17], v[82:85], v[150:153], v[2:17]
	ds_read2_b64 v[78:81], v246 offset0:8 offset1:10
	s_waitcnt lgkmcnt(6)
	v_mfma_f32_32x32x16_bf16 v[18:33], v[86:89], v[150:153], v[18:33]
	ds_read2_b64 v[82:85], v243 offset0:12 offset1:14
	s_waitcnt lgkmcnt(6)
	v_mfma_f32_32x32x16_bf16 v[34:49], v[90:93], v[150:153], v[34:49]
	ds_read2_b64 v[86:89], v244 offset0:12 offset1:14
	s_waitcnt lgkmcnt(6)
	v_mfma_f32_32x32x16_bf16 v[50:65], v[94:97], v[150:153], v[50:65]
	ds_read2_b64 v[90:93], v245 offset0:12 offset1:14
	s_waitcnt lgkmcnt(6)
	v_mfma_f32_32x32x16_bf16 v[2:17], v[66:69], v[154:157], v[2:17]
	ds_read2_b64 v[94:97], v246 offset0:12 offset1:14
	s_waitcnt lgkmcnt(6)
	v_mfma_f32_32x32x16_bf16 v[18:33], v[70:73], v[154:157], v[18:33]
	s_waitcnt lgkmcnt(5)
	v_mfma_f32_32x32x16_bf16 v[34:49], v[74:77], v[154:157], v[34:49]
	s_waitcnt lgkmcnt(4)
	v_mfma_f32_32x32x16_bf16 v[50:65], v[78:81], v[154:157], v[50:65]
	s_waitcnt lgkmcnt(3)
	v_mfma_f32_32x32x16_bf16 v[2:17], v[82:85], v[158:161], v[2:17]
	s_waitcnt lgkmcnt(2)
	v_mfma_f32_32x32x16_bf16 v[18:33], v[86:89], v[158:161], v[18:33]
	s_waitcnt lgkmcnt(1)
	v_mfma_f32_32x32x16_bf16 v[34:49], v[90:93], v[158:161], v[34:49]
	s_waitcnt lgkmcnt(0)
	v_mfma_f32_32x32x16_bf16 v[50:65], v[94:97], v[158:161], v[50:65]
.Lat_f_nopv:
	s_nop 15
	s_nop 7
	s_lshl_b32 s65, s34, 5
	s_cmp_lt_u32 s65, s28
	s_cbranch_scc0 .Lat_e_done
	ds_bpermute_b32 v0, v233, v237
	s_waitcnt lgkmcnt(0)
	v_add_f32_e32 v0, v0, v237
	v_rcp_f32_e32 v247, v0
	v_add_u32_e32 v0, s65, v240
	v_cmp_gt_u32_e32 vcc, s28, v0
	s_and_b64 vcc, vcc, s[2:3]
	s_and_saveexec_b64 s[4:5], vcc
	s_cbranch_execz .Lat_e_restore
	v_add_u32_e32 v0, s38, v234
	v_lshlrev_b32_e32 v0, 11, v0
	v_lshl_add_u32 v0, v241, 3, v0
	s_waitcnt vmcnt(0)
	v_lshlrev_b32_e32 v194, 16, v162
	v_and_b32_e32 v195, 0xffff0000, v162
	v_lshlrev_b32_e32 v196, 16, v163
	v_and_b32_e32 v197, 0xffff0000, v163
	v_mul_f32_e32 v2, v2, v247
	v_mul_f32_e32 v3, v3, v247
	v_mul_f32_e32 v4, v4, v247
	v_mul_f32_e32 v5, v5, v247
	v_mul_f32_e32 v2, v2, v194
	v_mul_f32_e32 v3, v3, v195
	v_mul_f32_e32 v4, v4, v196
	v_mul_f32_e32 v5, v5, v197
	v_cvt_pk_bf16_f32 v66, v2, v3
	v_cvt_pk_bf16_f32 v67, v4, v5
	global_store_dwordx2 v0, v[66:67], s[6:7] offset:0
	v_lshlrev_b32_e32 v194, 16, v164
	v_and_b32_e32 v195, 0xffff0000, v164
	v_lshlrev_b32_e32 v196, 16, v165
	v_and_b32_e32 v197, 0xffff0000, v165
	v_mul_f32_e32 v6, v6, v247
	v_mul_f32_e32 v7, v7, v247
	v_mul_f32_e32 v8, v8, v247
	v_mul_f32_e32 v9, v9, v247
	v_mul_f32_e32 v6, v6, v194
	v_mul_f32_e32 v7, v7, v195
	v_mul_f32_e32 v8, v8, v196
	v_mul_f32_e32 v9, v9, v197
	v_cvt_pk_bf16_f32 v68, v6, v7
	v_cvt_pk_bf16_f32 v69, v8, v9
	global_store_dwordx2 v0, v[68:69], s[6:7] offset:16
	v_lshlrev_b32_e32 v194, 16, v166
	v_and_b32_e32 v195, 0xffff0000, v166
	v_lshlrev_b32_e32 v196, 16, v167
	v_and_b32_e32 v197, 0xffff0000, v167
	v_mul_f32_e32 v10, v10, v247
	v_mul_f32_e32 v11, v11, v247
	v_mul_f32_e32 v12, v12, v247
	v_mul_f32_e32 v13, v13, v247
	v_mul_f32_e32 v10, v10, v194
	v_mul_f32_e32 v11, v11, v195
	v_mul_f32_e32 v12, v12, v196
	v_mul_f32_e32 v13, v13, v197
	v_cvt_pk_bf16_f32 v70, v10, v11
	v_cvt_pk_bf16_f32 v71, v12, v13
	global_store_dwordx2 v0, v[70:71], s[6:7] offset:32
	v_lshlrev_b32_e32 v194, 16, v168
	v_and_b32_e32 v195, 0xffff0000, v168
	v_lshlrev_b32_e32 v196, 16, v169
	v_and_b32_e32 v197, 0xffff0000, v169
	v_mul_f32_e32 v14, v14, v247
	v_mul_f32_e32 v15, v15, v247
	v_mul_f32_e32 v16, v16, v247
	v_mul_f32_e32 v17, v17, v247
	v_mul_f32_e32 v14, v14, v194
	v_mul_f32_e32 v15, v15, v195
	v_mul_f32_e32 v16, v16, v196
	v_mul_f32_e32 v17, v17, v197
	v_cvt_pk_bf16_f32 v72, v14, v15
	v_cvt_pk_bf16_f32 v73, v16, v17
	global_store_dwordx2 v0, v[72:73], s[6:7] offset:48
	v_lshlrev_b32_e32 v194, 16, v170
	v_and_b32_e32 v195, 0xffff0000, v170
	v_lshlrev_b32_e32 v196, 16, v171
	v_and_b32_e32 v197, 0xffff0000, v171
	v_mul_f32_e32 v18, v18, v247
	v_mul_f32_e32 v19, v19, v247
	v_mul_f32_e32 v20, v20, v247
	v_mul_f32_e32 v21, v21, v247
	v_mul_f32_e32 v18, v18, v194
	v_mul_f32_e32 v19, v19, v195
	v_mul_f32_e32 v20, v20, v196
	v_mul_f32_e32 v21, v21, v197
	v_cvt_pk_bf16_f32 v74, v18, v19
	v_cvt_pk_bf16_f32 v75, v20, v21
	global_store_dwordx2 v0, v[74:75], s[6:7] offset:64
	v_lshlrev_b32_e32 v194, 16, v172
	v_and_b32_e32 v195, 0xffff0000, v172
	v_lshlrev_b32_e32 v196, 16, v173
	v_and_b32_e32 v197, 0xffff0000, v173
	v_mul_f32_e32 v22, v22, v247
	v_mul_f32_e32 v23, v23, v247
	v_mul_f32_e32 v24, v24, v247
	v_mul_f32_e32 v25, v25, v247
	v_mul_f32_e32 v22, v22, v194
	v_mul_f32_e32 v23, v23, v195
	v_mul_f32_e32 v24, v24, v196
	v_mul_f32_e32 v25, v25, v197
	v_cvt_pk_bf16_f32 v76, v22, v23
	v_cvt_pk_bf16_f32 v77, v24, v25
	global_store_dwordx2 v0, v[76:77], s[6:7] offset:80
	v_lshlrev_b32_e32 v194, 16, v174
	v_and_b32_e32 v195, 0xffff0000, v174
	v_lshlrev_b32_e32 v196, 16, v175
	v_and_b32_e32 v197, 0xffff0000, v175
	v_mul_f32_e32 v26, v26, v247
	v_mul_f32_e32 v27, v27, v247
	v_mul_f32_e32 v28, v28, v247
	v_mul_f32_e32 v29, v29, v247
	v_mul_f32_e32 v26, v26, v194
	v_mul_f32_e32 v27, v27, v195
	v_mul_f32_e32 v28, v28, v196
	v_mul_f32_e32 v29, v29, v197
	v_cvt_pk_bf16_f32 v78, v26, v27
	v_cvt_pk_bf16_f32 v79, v28, v29
	global_store_dwordx2 v0, v[78:79], s[6:7] offset:96
	v_lshlrev_b32_e32 v194, 16, v176
	v_and_b32_e32 v195, 0xffff0000, v176
	v_lshlrev_b32_e32 v196, 16, v177
	v_and_b32_e32 v197, 0xffff0000, v177
	v_mul_f32_e32 v30, v30, v247
	v_mul_f32_e32 v31, v31, v247
	v_mul_f32_e32 v32, v32, v247
	v_mul_f32_e32 v33, v33, v247
	v_mul_f32_e32 v30, v30, v194
	v_mul_f32_e32 v31, v31, v195
	v_mul_f32_e32 v32, v32, v196
	v_mul_f32_e32 v33, v33, v197
	v_cvt_pk_bf16_f32 v80, v30, v31
	v_cvt_pk_bf16_f32 v81, v32, v33
	global_store_dwordx2 v0, v[80:81], s[6:7] offset:112
	v_lshlrev_b32_e32 v194, 16, v178
	v_and_b32_e32 v195, 0xffff0000, v178
	v_lshlrev_b32_e32 v196, 16, v179
	v_and_b32_e32 v197, 0xffff0000, v179
	v_mul_f32_e32 v34, v34, v247
	v_mul_f32_e32 v35, v35, v247
	v_mul_f32_e32 v36, v36, v247
	v_mul_f32_e32 v37, v37, v247
	v_mul_f32_e32 v34, v34, v194
	v_mul_f32_e32 v35, v35, v195
	v_mul_f32_e32 v36, v36, v196
	v_mul_f32_e32 v37, v37, v197
	v_cvt_pk_bf16_f32 v82, v34, v35
	v_cvt_pk_bf16_f32 v83, v36, v37
	global_store_dwordx2 v0, v[82:83], s[6:7] offset:128
	v_lshlrev_b32_e32 v194, 16, v180
	v_and_b32_e32 v195, 0xffff0000, v180
	v_lshlrev_b32_e32 v196, 16, v181
	v_and_b32_e32 v197, 0xffff0000, v181
	v_mul_f32_e32 v38, v38, v247
	v_mul_f32_e32 v39, v39, v247
	v_mul_f32_e32 v40, v40, v247
	v_mul_f32_e32 v41, v41, v247
	v_mul_f32_e32 v38, v38, v194
	v_mul_f32_e32 v39, v39, v195
	v_mul_f32_e32 v40, v40, v196
	v_mul_f32_e32 v41, v41, v197
	v_cvt_pk_bf16_f32 v84, v38, v39
	v_cvt_pk_bf16_f32 v85, v40, v41
	global_store_dwordx2 v0, v[84:85], s[6:7] offset:144
	v_lshlrev_b32_e32 v194, 16, v182
	v_and_b32_e32 v195, 0xffff0000, v182
	v_lshlrev_b32_e32 v196, 16, v183
	v_and_b32_e32 v197, 0xffff0000, v183
	v_mul_f32_e32 v42, v42, v247
	v_mul_f32_e32 v43, v43, v247
	v_mul_f32_e32 v44, v44, v247
	v_mul_f32_e32 v45, v45, v247
	v_mul_f32_e32 v42, v42, v194
	v_mul_f32_e32 v43, v43, v195
	v_mul_f32_e32 v44, v44, v196
	v_mul_f32_e32 v45, v45, v197
	v_cvt_pk_bf16_f32 v86, v42, v43
	v_cvt_pk_bf16_f32 v87, v44, v45
	global_store_dwordx2 v0, v[86:87], s[6:7] offset:160
	v_lshlrev_b32_e32 v194, 16, v184
	v_and_b32_e32 v195, 0xffff0000, v184
	v_lshlrev_b32_e32 v196, 16, v185
	v_and_b32_e32 v197, 0xffff0000, v185
	v_mul_f32_e32 v46, v46, v247
	v_mul_f32_e32 v47, v47, v247
	v_mul_f32_e32 v48, v48, v247
	v_mul_f32_e32 v49, v49, v247
	v_mul_f32_e32 v46, v46, v194
	v_mul_f32_e32 v47, v47, v195
	v_mul_f32_e32 v48, v48, v196
	v_mul_f32_e32 v49, v49, v197
	v_cvt_pk_bf16_f32 v88, v46, v47
	v_cvt_pk_bf16_f32 v89, v48, v49
	global_store_dwordx2 v0, v[88:89], s[6:7] offset:176
	v_lshlrev_b32_e32 v194, 16, v186
	v_and_b32_e32 v195, 0xffff0000, v186
	v_lshlrev_b32_e32 v196, 16, v187
	v_and_b32_e32 v197, 0xffff0000, v187
	v_mul_f32_e32 v50, v50, v247
	v_mul_f32_e32 v51, v51, v247
	v_mul_f32_e32 v52, v52, v247
	v_mul_f32_e32 v53, v53, v247
	v_mul_f32_e32 v50, v50, v194
	v_mul_f32_e32 v51, v51, v195
	v_mul_f32_e32 v52, v52, v196
	v_mul_f32_e32 v53, v53, v197
	v_cvt_pk_bf16_f32 v90, v50, v51
	v_cvt_pk_bf16_f32 v91, v52, v53
	global_store_dwordx2 v0, v[90:91], s[6:7] offset:192
	v_lshlrev_b32_e32 v194, 16, v188
	v_and_b32_e32 v195, 0xffff0000, v188
	v_lshlrev_b32_e32 v196, 16, v189
	v_and_b32_e32 v197, 0xffff0000, v189
	v_mul_f32_e32 v54, v54, v247
	v_mul_f32_e32 v55, v55, v247
	v_mul_f32_e32 v56, v56, v247
	v_mul_f32_e32 v57, v57, v247
	v_mul_f32_e32 v54, v54, v194
	v_mul_f32_e32 v55, v55, v195
	v_mul_f32_e32 v56, v56, v196
	v_mul_f32_e32 v57, v57, v197
	v_cvt_pk_bf16_f32 v92, v54, v55
	v_cvt_pk_bf16_f32 v93, v56, v57
	global_store_dwordx2 v0, v[92:93], s[6:7] offset:208
	v_lshlrev_b32_e32 v194, 16, v190
	v_and_b32_e32 v195, 0xffff0000, v190
	v_lshlrev_b32_e32 v196, 16, v191
	v_and_b32_e32 v197, 0xffff0000, v191
	v_mul_f32_e32 v58, v58, v247
	v_mul_f32_e32 v59, v59, v247
	v_mul_f32_e32 v60, v60, v247
	v_mul_f32_e32 v61, v61, v247
	v_mul_f32_e32 v58, v58, v194
	v_mul_f32_e32 v59, v59, v195
	v_mul_f32_e32 v60, v60, v196
	v_mul_f32_e32 v61, v61, v197
	v_cvt_pk_bf16_f32 v94, v58, v59
	v_cvt_pk_bf16_f32 v95, v60, v61
	global_store_dwordx2 v0, v[94:95], s[6:7] offset:224
	v_lshlrev_b32_e32 v194, 16, v192
	v_and_b32_e32 v195, 0xffff0000, v192
	v_lshlrev_b32_e32 v196, 16, v193
	v_and_b32_e32 v197, 0xffff0000, v193
	v_mul_f32_e32 v62, v62, v247
	v_mul_f32_e32 v63, v63, v247
	v_mul_f32_e32 v64, v64, v247
	v_mul_f32_e32 v65, v65, v247
	v_mul_f32_e32 v62, v62, v194
	v_mul_f32_e32 v63, v63, v195
	v_mul_f32_e32 v64, v64, v196
	v_mul_f32_e32 v65, v65, v197
	v_cvt_pk_bf16_f32 v96, v62, v63
	v_cvt_pk_bf16_f32 v97, v64, v65
	global_store_dwordx2 v0, v[96:97], s[6:7] offset:240
